# all w_in(1) transposes done by the 64 workgroups idle in the last round of layer 0's FFN-up GEMM; layer 1's normmod1 phase has no weight prep
# speedup vs baseline: 1.0033x; 1.0033x over previous
.LBB0_162:
	v_readlane_b32 s0, v252, 11
	s_add_i32 s0, s0, 7
	s_cmp_gt_u32 s0, 16
	s_waitcnt lgkmcnt(0)
	s_barrier
	v_readlane_b32 s1, v252, 12
	s_cbranch_scc1 .LBB0_200
	v_readlane_b32 s1, v253, 0
	s_mov_b32 s0, s49
	s_ashr_i32 s2, s0, 31
	v_readlane_b32 s6, v253, 3
	v_readlane_b32 s7, v253, 4
	s_add_u32 s12, s6, s0
	s_addc_u32 s13, s7, s2
	s_load_dwordx2 s[2:3], s[12:13], 0x48
	s_load_dwordx4 s[40:43], s[12:13], 0x60
	s_load_dwordx2 s[6:7], s[12:13], 0x70
	s_load_dwordx4 s[44:47], s[12:13], 0xd0
	v_readlane_b32 s0, v253, 56
	s_cmp_lt_i32 s1, s0
	v_readlane_b32 s14, v254, 0
	s_cselect_b64 s[12:13], -1, 0
	v_readlane_b32 s15, v254, 1
	s_or_b64 s[14:15], s[14:15], s[12:13]
	s_mov_b64 s[12:13], -1
	s_and_b64 vcc, exec, s[14:15]
	s_cbranch_vccnz .LBB0_182
	v_readlane_b32 s0, v253, 56
	s_sub_i32 s0, s1, s0
	s_cmpk_gt_i32 s0, 0x13f
	v_readlane_b32 s38, v253, 50
	v_readlane_b32 s39, v253, 59
	s_mov_b32 s78, 0xa02000
	s_mov_b32 s79, 0xa04000
	s_cbranch_scc1 .LBB0_181
	s_waitcnt lgkmcnt(0)
	s_add_u32 s16, s2, 0x1a00000
	s_addc_u32 s17, s3, 0
	s_lshl_b32 s12, s1, 9
	v_readlane_b32 s13, v253, 57
	s_add_i32 s30, s13, s12
	v_readlane_b32 s36, v254, 4
	s_cmpk_lg_u32 s36, 0x100
	s_cbranch_scc1 .LBB0_167
	s_branch .Lu1t_entry

.Lu1t_entry:
	s_mov_b32 s31, s38
	s_mov_b32 s36, s0
	s_cmpk_gt_i32 s36, 0x33f
	s_cbranch_scc1 .LBB0_181
	s_mov_b32 s30, s36
.Lu1t_klast:
	s_add_u32 s0, s30, s31
	s_cmpk_gt_u32 s0, 0x33f
	s_cbranch_scc1 .Lu1t_kdone
	s_mov_b32 s30, s0
	s_branch .Lu1t_klast
.Lu1t_kdone:
	v_lshrrev_b32_e32 v112, 4, v1
	v_and_b32_e32 v113, 15, v1
	v_lshlrev_b32_e32 v113, 4, v113
	v_mul_u32_u24_e32 v114, 0x104, v112
	v_add_u32_e32 v114, v114, v113
	v_lshrrev_b32_e32 v116, 3, v1
	v_and_b32_e32 v117, 7, v1
	v_mul_u32_u24_e32 v115, 0x1040, v117
	v_lshl_add_u32 v115, v116, 2, v115
	v_lshlrev_b32_e32 v117, 5, v117
	s_mul_i32 s48, s31, 0
	s_add_u32 s48, s48, s36
	s_min_u32 s48, s48, s30
	s_mov_b32 s0, s48
	s_mul_i32 s2, s0, 0x4ed
	s_lshr_b32 s2, s2, 17
	s_mul_i32 s3, s2, 0x68
	s_sub_u32 s3, s0, s3
	s_mul_i32 s14, s2, 0x340000
	s_lshl_b32 s0, s3, 8
	s_add_u32 s14, s14, s0
	s_add_u32 s6, s16, s14
	s_addc_u32 s7, s17, 0
	s_lshl_b32 s14, s3, 17
	s_lshl_b32 s0, s2, 8
	s_add_u32 s14, s14, s0
	s_add_u32 s12, s44, s14
	s_addc_u32 s13, s45, 0
	s_movk_i32 s18, 0x6800
	s_movk_i32 s19, 0x800
	v_mul_lo_u32 v123, v112, s18
	v_add_u32_e32 v118, v123, v113
	s_lshl_b32 vcc_lo, s18, 5
	v_add_u32_e32 v119, vcc_lo, v118
	v_add_u32_e32 v120, vcc_lo, v119
	v_add_u32_e32 v121, vcc_lo, v120
	global_load_dwordx4 v[40:43], v118, s[6:7]
	global_load_dwordx4 v[44:47], v119, s[6:7]
	global_load_dwordx4 v[48:51], v120, s[6:7]
	global_load_dwordx4 v[52:55], v121, s[6:7]
	s_mul_i32 s48, s31, 1
	s_add_u32 s48, s48, s36
	s_min_u32 s48, s48, s30
	s_mov_b32 s0, s48
	s_mul_i32 s2, s0, 0x4ed
	s_lshr_b32 s2, s2, 17
	s_mul_i32 s3, s2, 0x68
	s_sub_u32 s3, s0, s3
	s_mul_i32 s14, s2, 0x340000
	s_lshl_b32 s0, s3, 8
	s_add_u32 s14, s14, s0
	s_add_u32 s6, s16, s14
	s_addc_u32 s7, s17, 0
	s_lshl_b32 s14, s3, 17
	s_lshl_b32 s0, s2, 8
	s_add_u32 s14, s14, s0
	s_add_u32 s12, s44, s14
	s_addc_u32 s13, s45, 0
	s_movk_i32 s18, 0x6800
	s_movk_i32 s19, 0x800
	v_mul_lo_u32 v123, v112, s18
	v_add_u32_e32 v118, v123, v113
	s_lshl_b32 vcc_lo, s18, 5
	v_add_u32_e32 v119, vcc_lo, v118
	v_add_u32_e32 v120, vcc_lo, v119
	v_add_u32_e32 v121, vcc_lo, v120
	global_load_dwordx4 v[56:59], v118, s[6:7]
	global_load_dwordx4 v[60:63], v119, s[6:7]
	global_load_dwordx4 v[64:67], v120, s[6:7]
	global_load_dwordx4 v[68:71], v121, s[6:7]
	s_mul_i32 s48, s31, 2
	s_add_u32 s48, s48, s36
	s_min_u32 s48, s48, s30
	s_mov_b32 s0, s48
	s_mul_i32 s2, s0, 0x4ed
	s_lshr_b32 s2, s2, 17
	s_mul_i32 s3, s2, 0x68
	s_sub_u32 s3, s0, s3
	s_mul_i32 s14, s2, 0x340000
	s_lshl_b32 s0, s3, 8
	s_add_u32 s14, s14, s0
	s_add_u32 s6, s16, s14
	s_addc_u32 s7, s17, 0
	s_lshl_b32 s14, s3, 17
	s_lshl_b32 s0, s2, 8
	s_add_u32 s14, s14, s0
	s_add_u32 s12, s44, s14
	s_addc_u32 s13, s45, 0
	s_movk_i32 s18, 0x6800
	s_movk_i32 s19, 0x800
	v_mul_lo_u32 v123, v112, s18
	v_add_u32_e32 v118, v123, v113
	s_lshl_b32 vcc_lo, s18, 5
	v_add_u32_e32 v119, vcc_lo, v118
	v_add_u32_e32 v120, vcc_lo, v119
	v_add_u32_e32 v121, vcc_lo, v120
	global_load_dwordx4 v[72:75], v118, s[6:7]
	global_load_dwordx4 v[76:79], v119, s[6:7]
	global_load_dwordx4 v[80:83], v120, s[6:7]
	global_load_dwordx4 v[84:87], v121, s[6:7]
	s_mul_i32 s48, s31, 3
	s_add_u32 s48, s48, s36
	s_min_u32 s48, s48, s30
	s_mov_b32 s0, s48
	s_mul_i32 s2, s0, 0x4ed
	s_lshr_b32 s2, s2, 17
	s_mul_i32 s3, s2, 0x68
	s_sub_u32 s3, s0, s3
	s_mul_i32 s14, s2, 0x340000
	s_lshl_b32 s0, s3, 8
	s_add_u32 s14, s14, s0
	s_add_u32 s6, s16, s14
	s_addc_u32 s7, s17, 0
	s_lshl_b32 s14, s3, 17
	s_lshl_b32 s0, s2, 8
	s_add_u32 s14, s14, s0
	s_add_u32 s12, s44, s14
	s_addc_u32 s13, s45, 0
	s_movk_i32 s18, 0x6800
	s_movk_i32 s19, 0x800
	v_mul_lo_u32 v123, v112, s18
	v_add_u32_e32 v118, v123, v113
	s_lshl_b32 vcc_lo, s18, 5
	v_add_u32_e32 v119, vcc_lo, v118
	v_add_u32_e32 v120, vcc_lo, v119
	v_add_u32_e32 v121, vcc_lo, v120
	global_load_dwordx4 v[124:127], v118, s[6:7]
	global_load_dwordx4 v[128:131], v119, s[6:7]
	global_load_dwordx4 v[132:135], v120, s[6:7]
	global_load_dwordx4 v[136:139], v121, s[6:7]
	s_waitcnt vmcnt(12)
	ds_write_b32 v114, v40 offset:0
	ds_write_b32 v114, v41 offset:4
	ds_write_b32 v114, v42 offset:8
	ds_write_b32 v114, v43 offset:12
	ds_write_b32 v114, v44 offset:8320
	ds_write_b32 v114, v45 offset:8324
	ds_write_b32 v114, v46 offset:8328
	ds_write_b32 v114, v47 offset:8332
	ds_write_b32 v114, v48 offset:16640
	ds_write_b32 v114, v49 offset:16644
	ds_write_b32 v114, v50 offset:16648
	ds_write_b32 v114, v51 offset:16652
	ds_write_b32 v114, v52 offset:24960
	ds_write_b32 v114, v53 offset:24964
	ds_write_b32 v114, v54 offset:24968
	ds_write_b32 v114, v55 offset:24972
	s_waitcnt lgkmcnt(0)
	s_barrier
	ds_read_b32 v88, v115 offset:0
	ds_read_b32 v89, v115 offset:260
	ds_read_b32 v90, v115 offset:520
	ds_read_b32 v91, v115 offset:780
	ds_read_b32 v92, v115 offset:1040
	ds_read_b32 v93, v115 offset:1300
	ds_read_b32 v94, v115 offset:1560
	ds_read_b32 v95, v115 offset:1820
	ds_read_b32 v96, v115 offset:2080
	ds_read_b32 v97, v115 offset:2340
	ds_read_b32 v98, v115 offset:2600
	ds_read_b32 v99, v115 offset:2860
	ds_read_b32 v100, v115 offset:3120
	ds_read_b32 v101, v115 offset:3380
	ds_read_b32 v102, v115 offset:3640
	ds_read_b32 v103, v115 offset:3900
	s_mul_i32 s48, s31, 0
	s_add_u32 s48, s48, s36
	s_min_u32 s48, s48, s30
	s_mov_b32 s0, s48
	s_mul_i32 s2, s0, 0x4ed
	s_lshr_b32 s2, s2, 17
	s_mul_i32 s3, s2, 0x68
	s_sub_u32 s3, s0, s3
	s_mul_i32 s14, s2, 0x340000
	s_lshl_b32 s0, s3, 8
	s_add_u32 s14, s14, s0
	s_add_u32 s6, s16, s14
	s_addc_u32 s7, s17, 0
	s_lshl_b32 s14, s3, 17
	s_lshl_b32 s0, s2, 8
	s_add_u32 s14, s14, s0
	s_add_u32 s12, s44, s14
	s_addc_u32 s13, s45, 0
	s_movk_i32 s18, 0x6800
	s_movk_i32 s19, 0x800
	v_mul_lo_u32 v122, v116, s19
	v_add_u32_e32 v122, v122, v117
	s_waitcnt lgkmcnt(0)
	v_cvt_pk_bf16_f32 v104, v88, v89
	v_cvt_pk_bf16_f32 v105, v90, v91
	v_cvt_pk_bf16_f32 v106, v92, v93
	v_cvt_pk_bf16_f32 v107, v94, v95
	v_cvt_pk_bf16_f32 v108, v96, v97
	v_cvt_pk_bf16_f32 v109, v98, v99
	v_cvt_pk_bf16_f32 v110, v100, v101
	v_cvt_pk_bf16_f32 v111, v102, v103
	global_store_dwordx4 v122, v[104:107], s[12:13]
	global_store_dwordx4 v122, v[108:111], s[12:13] offset:16
	s_nop 1
	s_mul_i32 s48, s31, 1
	s_add_u32 s48, s48, s36
	s_cmp_gt_u32 s48, s30
	s_cbranch_scc1 .Lu1t_alldone
	s_mul_i32 s48, s31, 4
	s_add_u32 s48, s48, s36
	s_min_u32 s48, s48, s30
	s_mov_b32 s0, s48
	s_mul_i32 s2, s0, 0x4ed
	s_lshr_b32 s2, s2, 17
	s_mul_i32 s3, s2, 0x68
	s_sub_u32 s3, s0, s3
	s_mul_i32 s14, s2, 0x340000
	s_lshl_b32 s0, s3, 8
	s_add_u32 s14, s14, s0
	s_add_u32 s6, s16, s14
	s_addc_u32 s7, s17, 0
	s_lshl_b32 s14, s3, 17
	s_lshl_b32 s0, s2, 8
	s_add_u32 s14, s14, s0
	s_add_u32 s12, s44, s14
	s_addc_u32 s13, s45, 0
	s_movk_i32 s18, 0x6800
	s_movk_i32 s19, 0x800
	v_mul_lo_u32 v123, v112, s18
	v_add_u32_e32 v118, v123, v113
	s_lshl_b32 vcc_lo, s18, 5
	v_add_u32_e32 v119, vcc_lo, v118
	v_add_u32_e32 v120, vcc_lo, v119
	v_add_u32_e32 v121, vcc_lo, v120
	global_load_dwordx4 v[40:43], v118, s[6:7]
	global_load_dwordx4 v[44:47], v119, s[6:7]
	global_load_dwordx4 v[48:51], v120, s[6:7]
	global_load_dwordx4 v[52:55], v121, s[6:7]
	s_waitcnt vmcnt(14)
	ds_write_b32 v114, v56 offset:33792
	ds_write_b32 v114, v57 offset:33796
	ds_write_b32 v114, v58 offset:33800
	ds_write_b32 v114, v59 offset:33804
	ds_write_b32 v114, v60 offset:42112
	ds_write_b32 v114, v61 offset:42116
	ds_write_b32 v114, v62 offset:42120
	ds_write_b32 v114, v63 offset:42124
	ds_write_b32 v114, v64 offset:50432
	ds_write_b32 v114, v65 offset:50436
	ds_write_b32 v114, v66 offset:50440
	ds_write_b32 v114, v67 offset:50444
	ds_write_b32 v114, v68 offset:58752
	ds_write_b32 v114, v69 offset:58756
	ds_write_b32 v114, v70 offset:58760
	ds_write_b32 v114, v71 offset:58764
	s_waitcnt lgkmcnt(0)
	s_barrier
	ds_read_b32 v88, v115 offset:33792
	ds_read_b32 v89, v115 offset:34052
	ds_read_b32 v90, v115 offset:34312
	ds_read_b32 v91, v115 offset:34572
	ds_read_b32 v92, v115 offset:34832
	ds_read_b32 v93, v115 offset:35092
	ds_read_b32 v94, v115 offset:35352
	ds_read_b32 v95, v115 offset:35612
	ds_read_b32 v96, v115 offset:35872
	ds_read_b32 v97, v115 offset:36132
	ds_read_b32 v98, v115 offset:36392
	ds_read_b32 v99, v115 offset:36652
	ds_read_b32 v100, v115 offset:36912
	ds_read_b32 v101, v115 offset:37172
	ds_read_b32 v102, v115 offset:37432
	ds_read_b32 v103, v115 offset:37692
	s_mul_i32 s48, s31, 1
	s_add_u32 s48, s48, s36
	s_min_u32 s48, s48, s30
	s_mov_b32 s0, s48
	s_mul_i32 s2, s0, 0x4ed
	s_lshr_b32 s2, s2, 17
	s_mul_i32 s3, s2, 0x68
	s_sub_u32 s3, s0, s3
	s_mul_i32 s14, s2, 0x340000
	s_lshl_b32 s0, s3, 8
	s_add_u32 s14, s14, s0
	s_add_u32 s6, s16, s14
	s_addc_u32 s7, s17, 0
	s_lshl_b32 s14, s3, 17
	s_lshl_b32 s0, s2, 8
	s_add_u32 s14, s14, s0
	s_add_u32 s12, s44, s14
	s_addc_u32 s13, s45, 0
	s_movk_i32 s18, 0x6800
	s_movk_i32 s19, 0x800
	v_mul_lo_u32 v122, v116, s19
	v_add_u32_e32 v122, v122, v117
	s_waitcnt lgkmcnt(0)
	v_cvt_pk_bf16_f32 v104, v88, v89
	v_cvt_pk_bf16_f32 v105, v90, v91
	v_cvt_pk_bf16_f32 v106, v92, v93
	v_cvt_pk_bf16_f32 v107, v94, v95
	v_cvt_pk_bf16_f32 v108, v96, v97
	v_cvt_pk_bf16_f32 v109, v98, v99
	v_cvt_pk_bf16_f32 v110, v100, v101
	v_cvt_pk_bf16_f32 v111, v102, v103
	global_store_dwordx4 v122, v[104:107], s[12:13]
	global_store_dwordx4 v122, v[108:111], s[12:13] offset:16
	s_nop 1
	s_mul_i32 s48, s31, 2
	s_add_u32 s48, s48, s36
	s_cmp_gt_u32 s48, s30
	s_cbranch_scc1 .Lu1t_alldone
	s_mul_i32 s48, s31, 5
	s_add_u32 s48, s48, s36
	s_min_u32 s48, s48, s30
	s_mov_b32 s0, s48
	s_mul_i32 s2, s0, 0x4ed
	s_lshr_b32 s2, s2, 17
	s_mul_i32 s3, s2, 0x68
	s_sub_u32 s3, s0, s3
	s_mul_i32 s14, s2, 0x340000
	s_lshl_b32 s0, s3, 8
	s_add_u32 s14, s14, s0
	s_add_u32 s6, s16, s14
	s_addc_u32 s7, s17, 0
	s_lshl_b32 s14, s3, 17
	s_lshl_b32 s0, s2, 8
	s_add_u32 s14, s14, s0
	s_add_u32 s12, s44, s14
	s_addc_u32 s13, s45, 0
	s_movk_i32 s18, 0x6800
	s_movk_i32 s19, 0x800
	v_mul_lo_u32 v123, v112, s18
	v_add_u32_e32 v118, v123, v113
	s_lshl_b32 vcc_lo, s18, 5
	v_add_u32_e32 v119, vcc_lo, v118
	v_add_u32_e32 v120, vcc_lo, v119
	v_add_u32_e32 v121, vcc_lo, v120
	global_load_dwordx4 v[56:59], v118, s[6:7]
	global_load_dwordx4 v[60:63], v119, s[6:7]
	global_load_dwordx4 v[64:67], v120, s[6:7]
	global_load_dwordx4 v[68:71], v121, s[6:7]
	s_waitcnt vmcnt(16)
	ds_write_b32 v114, v72 offset:0
	ds_write_b32 v114, v73 offset:4
	ds_write_b32 v114, v74 offset:8
	ds_write_b32 v114, v75 offset:12
	ds_write_b32 v114, v76 offset:8320
	ds_write_b32 v114, v77 offset:8324
	ds_write_b32 v114, v78 offset:8328
	ds_write_b32 v114, v79 offset:8332
	ds_write_b32 v114, v80 offset:16640
	ds_write_b32 v114, v81 offset:16644
	ds_write_b32 v114, v82 offset:16648
	ds_write_b32 v114, v83 offset:16652
	ds_write_b32 v114, v84 offset:24960
	ds_write_b32 v114, v85 offset:24964
	ds_write_b32 v114, v86 offset:24968
	ds_write_b32 v114, v87 offset:24972
	s_waitcnt lgkmcnt(0)
	s_barrier
	ds_read_b32 v88, v115 offset:0
	ds_read_b32 v89, v115 offset:260
	ds_read_b32 v90, v115 offset:520
	ds_read_b32 v91, v115 offset:780
	ds_read_b32 v92, v115 offset:1040
	ds_read_b32 v93, v115 offset:1300
	ds_read_b32 v94, v115 offset:1560
	ds_read_b32 v95, v115 offset:1820
	ds_read_b32 v96, v115 offset:2080
	ds_read_b32 v97, v115 offset:2340
	ds_read_b32 v98, v115 offset:2600
	ds_read_b32 v99, v115 offset:2860
	ds_read_b32 v100, v115 offset:3120
	ds_read_b32 v101, v115 offset:3380
	ds_read_b32 v102, v115 offset:3640
	ds_read_b32 v103, v115 offset:3900
	s_mul_i32 s48, s31, 2
	s_add_u32 s48, s48, s36
	s_min_u32 s48, s48, s30
	s_mov_b32 s0, s48
	s_mul_i32 s2, s0, 0x4ed
	s_lshr_b32 s2, s2, 17
	s_mul_i32 s3, s2, 0x68
	s_sub_u32 s3, s0, s3
	s_mul_i32 s14, s2, 0x340000
	s_lshl_b32 s0, s3, 8
	s_add_u32 s14, s14, s0
	s_add_u32 s6, s16, s14
	s_addc_u32 s7, s17, 0
	s_lshl_b32 s14, s3, 17
	s_lshl_b32 s0, s2, 8
	s_add_u32 s14, s14, s0
	s_add_u32 s12, s44, s14
	s_addc_u32 s13, s45, 0
	s_movk_i32 s18, 0x6800
	s_movk_i32 s19, 0x800
	v_mul_lo_u32 v122, v116, s19
	v_add_u32_e32 v122, v122, v117
	s_waitcnt lgkmcnt(0)
	v_cvt_pk_bf16_f32 v104, v88, v89
	v_cvt_pk_bf16_f32 v105, v90, v91
	v_cvt_pk_bf16_f32 v106, v92, v93
	v_cvt_pk_bf16_f32 v107, v94, v95
	v_cvt_pk_bf16_f32 v108, v96, v97
	v_cvt_pk_bf16_f32 v109, v98, v99
	v_cvt_pk_bf16_f32 v110, v100, v101
	v_cvt_pk_bf16_f32 v111, v102, v103
	global_store_dwordx4 v122, v[104:107], s[12:13]
	global_store_dwordx4 v122, v[108:111], s[12:13] offset:16
	s_nop 1
	s_mul_i32 s48, s31, 3
	s_add_u32 s48, s48, s36
	s_cmp_gt_u32 s48, s30
	s_cbranch_scc1 .Lu1t_alldone
	s_mul_i32 s48, s31, 6
	s_add_u32 s48, s48, s36
	s_min_u32 s48, s48, s30
	s_mov_b32 s0, s48
	s_mul_i32 s2, s0, 0x4ed
	s_lshr_b32 s2, s2, 17
	s_mul_i32 s3, s2, 0x68
	s_sub_u32 s3, s0, s3
	s_mul_i32 s14, s2, 0x340000
	s_lshl_b32 s0, s3, 8
	s_add_u32 s14, s14, s0
	s_add_u32 s6, s16, s14
	s_addc_u32 s7, s17, 0
	s_lshl_b32 s14, s3, 17
	s_lshl_b32 s0, s2, 8
	s_add_u32 s14, s14, s0
	s_add_u32 s12, s44, s14
	s_addc_u32 s13, s45, 0
	s_movk_i32 s18, 0x6800
	s_movk_i32 s19, 0x800
	v_mul_lo_u32 v123, v112, s18
	v_add_u32_e32 v118, v123, v113
	s_lshl_b32 vcc_lo, s18, 5
	v_add_u32_e32 v119, vcc_lo, v118
	v_add_u32_e32 v120, vcc_lo, v119
	v_add_u32_e32 v121, vcc_lo, v120
	global_load_dwordx4 v[72:75], v118, s[6:7]
	global_load_dwordx4 v[76:79], v119, s[6:7]
	global_load_dwordx4 v[80:83], v120, s[6:7]
	global_load_dwordx4 v[84:87], v121, s[6:7]
	s_waitcnt vmcnt(18)
	ds_write_b32 v114, v124 offset:33792
	ds_write_b32 v114, v125 offset:33796
	ds_write_b32 v114, v126 offset:33800
	ds_write_b32 v114, v127 offset:33804
	ds_write_b32 v114, v128 offset:42112
	ds_write_b32 v114, v129 offset:42116
	ds_write_b32 v114, v130 offset:42120
	ds_write_b32 v114, v131 offset:42124
	ds_write_b32 v114, v132 offset:50432
	ds_write_b32 v114, v133 offset:50436
	ds_write_b32 v114, v134 offset:50440
	ds_write_b32 v114, v135 offset:50444
	ds_write_b32 v114, v136 offset:58752
	ds_write_b32 v114, v137 offset:58756
	ds_write_b32 v114, v138 offset:58760
	ds_write_b32 v114, v139 offset:58764
	s_waitcnt lgkmcnt(0)
	s_barrier
	ds_read_b32 v88, v115 offset:33792
	ds_read_b32 v89, v115 offset:34052
	ds_read_b32 v90, v115 offset:34312
	ds_read_b32 v91, v115 offset:34572
	ds_read_b32 v92, v115 offset:34832
	ds_read_b32 v93, v115 offset:35092
	ds_read_b32 v94, v115 offset:35352
	ds_read_b32 v95, v115 offset:35612
	ds_read_b32 v96, v115 offset:35872
	ds_read_b32 v97, v115 offset:36132
	ds_read_b32 v98, v115 offset:36392
	ds_read_b32 v99, v115 offset:36652
	ds_read_b32 v100, v115 offset:36912
	ds_read_b32 v101, v115 offset:37172
	ds_read_b32 v102, v115 offset:37432
	ds_read_b32 v103, v115 offset:37692
	s_mul_i32 s48, s31, 3
	s_add_u32 s48, s48, s36
	s_min_u32 s48, s48, s30
	s_mov_b32 s0, s48
	s_mul_i32 s2, s0, 0x4ed
	s_lshr_b32 s2, s2, 17
	s_mul_i32 s3, s2, 0x68
	s_sub_u32 s3, s0, s3
	s_mul_i32 s14, s2, 0x340000
	s_lshl_b32 s0, s3, 8
	s_add_u32 s14, s14, s0
	s_add_u32 s6, s16, s14
	s_addc_u32 s7, s17, 0
	s_lshl_b32 s14, s3, 17
	s_lshl_b32 s0, s2, 8
	s_add_u32 s14, s14, s0
	s_add_u32 s12, s44, s14
	s_addc_u32 s13, s45, 0
	s_movk_i32 s18, 0x6800
	s_movk_i32 s19, 0x800
	v_mul_lo_u32 v122, v116, s19
	v_add_u32_e32 v122, v122, v117
	s_waitcnt lgkmcnt(0)
	v_cvt_pk_bf16_f32 v104, v88, v89
	v_cvt_pk_bf16_f32 v105, v90, v91
	v_cvt_pk_bf16_f32 v106, v92, v93
	v_cvt_pk_bf16_f32 v107, v94, v95
	v_cvt_pk_bf16_f32 v108, v96, v97
	v_cvt_pk_bf16_f32 v109, v98, v99
	v_cvt_pk_bf16_f32 v110, v100, v101
	v_cvt_pk_bf16_f32 v111, v102, v103
	global_store_dwordx4 v122, v[104:107], s[12:13]
	global_store_dwordx4 v122, v[108:111], s[12:13] offset:16
	s_nop 1
	s_mul_i32 s48, s31, 4
	s_add_u32 s48, s48, s36
	s_cmp_gt_u32 s48, s30
	s_cbranch_scc1 .Lu1t_alldone
	s_mul_i32 s48, s31, 7
	s_add_u32 s48, s48, s36
	s_min_u32 s48, s48, s30
	s_mov_b32 s0, s48
	s_mul_i32 s2, s0, 0x4ed
	s_lshr_b32 s2, s2, 17
	s_mul_i32 s3, s2, 0x68
	s_sub_u32 s3, s0, s3
	s_mul_i32 s14, s2, 0x340000
	s_lshl_b32 s0, s3, 8
	s_add_u32 s14, s14, s0
	s_add_u32 s6, s16, s14
	s_addc_u32 s7, s17, 0
	s_lshl_b32 s14, s3, 17
	s_lshl_b32 s0, s2, 8
	s_add_u32 s14, s14, s0
	s_add_u32 s12, s44, s14
	s_addc_u32 s13, s45, 0
	s_movk_i32 s18, 0x6800
	s_movk_i32 s19, 0x800
	v_mul_lo_u32 v123, v112, s18
	v_add_u32_e32 v118, v123, v113
	s_lshl_b32 vcc_lo, s18, 5
	v_add_u32_e32 v119, vcc_lo, v118
	v_add_u32_e32 v120, vcc_lo, v119
	v_add_u32_e32 v121, vcc_lo, v120
	global_load_dwordx4 v[124:127], v118, s[6:7]
	global_load_dwordx4 v[128:131], v119, s[6:7]
	global_load_dwordx4 v[132:135], v120, s[6:7]
	global_load_dwordx4 v[136:139], v121, s[6:7]
	s_waitcnt vmcnt(18)
	ds_write_b32 v114, v40 offset:0
	ds_write_b32 v114, v41 offset:4
	ds_write_b32 v114, v42 offset:8
	ds_write_b32 v114, v43 offset:12
	ds_write_b32 v114, v44 offset:8320
	ds_write_b32 v114, v45 offset:8324
	ds_write_b32 v114, v46 offset:8328
	ds_write_b32 v114, v47 offset:8332
	ds_write_b32 v114, v48 offset:16640
	ds_write_b32 v114, v49 offset:16644
	ds_write_b32 v114, v50 offset:16648
	ds_write_b32 v114, v51 offset:16652
	ds_write_b32 v114, v52 offset:24960
	ds_write_b32 v114, v53 offset:24964
	ds_write_b32 v114, v54 offset:24968
	ds_write_b32 v114, v55 offset:24972
	s_waitcnt lgkmcnt(0)
	s_barrier
	ds_read_b32 v88, v115 offset:0
	ds_read_b32 v89, v115 offset:260
	ds_read_b32 v90, v115 offset:520
	ds_read_b32 v91, v115 offset:780
	ds_read_b32 v92, v115 offset:1040
	ds_read_b32 v93, v115 offset:1300
	ds_read_b32 v94, v115 offset:1560
	ds_read_b32 v95, v115 offset:1820
	ds_read_b32 v96, v115 offset:2080
	ds_read_b32 v97, v115 offset:2340
	ds_read_b32 v98, v115 offset:2600
	ds_read_b32 v99, v115 offset:2860
	ds_read_b32 v100, v115 offset:3120
	ds_read_b32 v101, v115 offset:3380
	ds_read_b32 v102, v115 offset:3640
	ds_read_b32 v103, v115 offset:3900
	s_mul_i32 s48, s31, 4
	s_add_u32 s48, s48, s36
	s_min_u32 s48, s48, s30
	s_mov_b32 s0, s48
	s_mul_i32 s2, s0, 0x4ed
	s_lshr_b32 s2, s2, 17
	s_mul_i32 s3, s2, 0x68
	s_sub_u32 s3, s0, s3
	s_mul_i32 s14, s2, 0x340000
	s_lshl_b32 s0, s3, 8
	s_add_u32 s14, s14, s0
	s_add_u32 s6, s16, s14
	s_addc_u32 s7, s17, 0
	s_lshl_b32 s14, s3, 17
	s_lshl_b32 s0, s2, 8
	s_add_u32 s14, s14, s0
	s_add_u32 s12, s44, s14
	s_addc_u32 s13, s45, 0
	s_movk_i32 s18, 0x6800
	s_movk_i32 s19, 0x800
	v_mul_lo_u32 v122, v116, s19
	v_add_u32_e32 v122, v122, v117
	s_waitcnt lgkmcnt(0)
	v_cvt_pk_bf16_f32 v104, v88, v89
	v_cvt_pk_bf16_f32 v105, v90, v91
	v_cvt_pk_bf16_f32 v106, v92, v93
	v_cvt_pk_bf16_f32 v107, v94, v95
	v_cvt_pk_bf16_f32 v108, v96, v97
	v_cvt_pk_bf16_f32 v109, v98, v99
	v_cvt_pk_bf16_f32 v110, v100, v101
	v_cvt_pk_bf16_f32 v111, v102, v103
	global_store_dwordx4 v122, v[104:107], s[12:13]
	global_store_dwordx4 v122, v[108:111], s[12:13] offset:16
	s_nop 1
	s_mul_i32 s48, s31, 5
	s_add_u32 s48, s48, s36
	s_cmp_gt_u32 s48, s30
	s_cbranch_scc1 .Lu1t_alldone
	s_mul_i32 s48, s31, 8
	s_add_u32 s48, s48, s36
	s_min_u32 s48, s48, s30
	s_mov_b32 s0, s48
	s_mul_i32 s2, s0, 0x4ed
	s_lshr_b32 s2, s2, 17
	s_mul_i32 s3, s2, 0x68
	s_sub_u32 s3, s0, s3
	s_mul_i32 s14, s2, 0x340000
	s_lshl_b32 s0, s3, 8
	s_add_u32 s14, s14, s0
	s_add_u32 s6, s16, s14
	s_addc_u32 s7, s17, 0
	s_lshl_b32 s14, s3, 17
	s_lshl_b32 s0, s2, 8
	s_add_u32 s14, s14, s0
	s_add_u32 s12, s44, s14
	s_addc_u32 s13, s45, 0
	s_movk_i32 s18, 0x6800
	s_movk_i32 s19, 0x800
	v_mul_lo_u32 v123, v112, s18
	v_add_u32_e32 v118, v123, v113
	s_lshl_b32 vcc_lo, s18, 5
	v_add_u32_e32 v119, vcc_lo, v118
	v_add_u32_e32 v120, vcc_lo, v119
	v_add_u32_e32 v121, vcc_lo, v120
	global_load_dwordx4 v[40:43], v118, s[6:7]
	global_load_dwordx4 v[44:47], v119, s[6:7]
	global_load_dwordx4 v[48:51], v120, s[6:7]
	global_load_dwordx4 v[52:55], v121, s[6:7]
	s_waitcnt vmcnt(18)
	ds_write_b32 v114, v56 offset:33792
	ds_write_b32 v114, v57 offset:33796
	ds_write_b32 v114, v58 offset:33800
	ds_write_b32 v114, v59 offset:33804
	ds_write_b32 v114, v60 offset:42112
	ds_write_b32 v114, v61 offset:42116
	ds_write_b32 v114, v62 offset:42120
	ds_write_b32 v114, v63 offset:42124
	ds_write_b32 v114, v64 offset:50432
	ds_write_b32 v114, v65 offset:50436
	ds_write_b32 v114, v66 offset:50440
	ds_write_b32 v114, v67 offset:50444
	ds_write_b32 v114, v68 offset:58752
	ds_write_b32 v114, v69 offset:58756
	ds_write_b32 v114, v70 offset:58760
	ds_write_b32 v114, v71 offset:58764
	s_waitcnt lgkmcnt(0)
	s_barrier
	ds_read_b32 v88, v115 offset:33792
	ds_read_b32 v89, v115 offset:34052
	ds_read_b32 v90, v115 offset:34312
	ds_read_b32 v91, v115 offset:34572
	ds_read_b32 v92, v115 offset:34832
	ds_read_b32 v93, v115 offset:35092
	ds_read_b32 v94, v115 offset:35352
	ds_read_b32 v95, v115 offset:35612
	ds_read_b32 v96, v115 offset:35872
	ds_read_b32 v97, v115 offset:36132
	ds_read_b32 v98, v115 offset:36392
	ds_read_b32 v99, v115 offset:36652
	ds_read_b32 v100, v115 offset:36912
	ds_read_b32 v101, v115 offset:37172
	ds_read_b32 v102, v115 offset:37432
	ds_read_b32 v103, v115 offset:37692
	s_mul_i32 s48, s31, 5
	s_add_u32 s48, s48, s36
	s_min_u32 s48, s48, s30
	s_mov_b32 s0, s48
	s_mul_i32 s2, s0, 0x4ed
	s_lshr_b32 s2, s2, 17
	s_mul_i32 s3, s2, 0x68
	s_sub_u32 s3, s0, s3
	s_mul_i32 s14, s2, 0x340000
	s_lshl_b32 s0, s3, 8
	s_add_u32 s14, s14, s0
	s_add_u32 s6, s16, s14
	s_addc_u32 s7, s17, 0
	s_lshl_b32 s14, s3, 17
	s_lshl_b32 s0, s2, 8
	s_add_u32 s14, s14, s0
	s_add_u32 s12, s44, s14
	s_addc_u32 s13, s45, 0
	s_movk_i32 s18, 0x6800
	s_movk_i32 s19, 0x800
	v_mul_lo_u32 v122, v116, s19
	v_add_u32_e32 v122, v122, v117
	s_waitcnt lgkmcnt(0)
	v_cvt_pk_bf16_f32 v104, v88, v89
	v_cvt_pk_bf16_f32 v105, v90, v91
	v_cvt_pk_bf16_f32 v106, v92, v93
	v_cvt_pk_bf16_f32 v107, v94, v95
	v_cvt_pk_bf16_f32 v108, v96, v97
	v_cvt_pk_bf16_f32 v109, v98, v99
	v_cvt_pk_bf16_f32 v110, v100, v101
	v_cvt_pk_bf16_f32 v111, v102, v103
	global_store_dwordx4 v122, v[104:107], s[12:13]
	global_store_dwordx4 v122, v[108:111], s[12:13] offset:16
	s_nop 1
	s_mul_i32 s48, s31, 6
	s_add_u32 s48, s48, s36
	s_cmp_gt_u32 s48, s30
	s_cbranch_scc1 .Lu1t_alldone
	s_mul_i32 s48, s31, 9
	s_add_u32 s48, s48, s36
	s_min_u32 s48, s48, s30
	s_mov_b32 s0, s48
	s_mul_i32 s2, s0, 0x4ed
	s_lshr_b32 s2, s2, 17
	s_mul_i32 s3, s2, 0x68
	s_sub_u32 s3, s0, s3
	s_mul_i32 s14, s2, 0x340000
	s_lshl_b32 s0, s3, 8
	s_add_u32 s14, s14, s0
	s_add_u32 s6, s16, s14
	s_addc_u32 s7, s17, 0
	s_lshl_b32 s14, s3, 17
	s_lshl_b32 s0, s2, 8
	s_add_u32 s14, s14, s0
	s_add_u32 s12, s44, s14
	s_addc_u32 s13, s45, 0
	s_movk_i32 s18, 0x6800
	s_movk_i32 s19, 0x800
	v_mul_lo_u32 v123, v112, s18
	v_add_u32_e32 v118, v123, v113
	s_lshl_b32 vcc_lo, s18, 5
	v_add_u32_e32 v119, vcc_lo, v118
	v_add_u32_e32 v120, vcc_lo, v119
	v_add_u32_e32 v121, vcc_lo, v120
	global_load_dwordx4 v[56:59], v118, s[6:7]
	global_load_dwordx4 v[60:63], v119, s[6:7]
	global_load_dwordx4 v[64:67], v120, s[6:7]
	global_load_dwordx4 v[68:71], v121, s[6:7]
	s_waitcnt vmcnt(18)
	ds_write_b32 v114, v72 offset:0
	ds_write_b32 v114, v73 offset:4
	ds_write_b32 v114, v74 offset:8
	ds_write_b32 v114, v75 offset:12
	ds_write_b32 v114, v76 offset:8320
	ds_write_b32 v114, v77 offset:8324
	ds_write_b32 v114, v78 offset:8328
	ds_write_b32 v114, v79 offset:8332
	ds_write_b32 v114, v80 offset:16640
	ds_write_b32 v114, v81 offset:16644
	ds_write_b32 v114, v82 offset:16648
	ds_write_b32 v114, v83 offset:16652
	ds_write_b32 v114, v84 offset:24960
	ds_write_b32 v114, v85 offset:24964
	ds_write_b32 v114, v86 offset:24968
	ds_write_b32 v114, v87 offset:24972
	s_waitcnt lgkmcnt(0)
	s_barrier
	ds_read_b32 v88, v115 offset:0
	ds_read_b32 v89, v115 offset:260
	ds_read_b32 v90, v115 offset:520
	ds_read_b32 v91, v115 offset:780
	ds_read_b32 v92, v115 offset:1040
	ds_read_b32 v93, v115 offset:1300
	ds_read_b32 v94, v115 offset:1560
	ds_read_b32 v95, v115 offset:1820
	ds_read_b32 v96, v115 offset:2080
	ds_read_b32 v97, v115 offset:2340
	ds_read_b32 v98, v115 offset:2600
	ds_read_b32 v99, v115 offset:2860
	ds_read_b32 v100, v115 offset:3120
	ds_read_b32 v101, v115 offset:3380
	ds_read_b32 v102, v115 offset:3640
	ds_read_b32 v103, v115 offset:3900
	s_mul_i32 s48, s31, 6
	s_add_u32 s48, s48, s36
	s_min_u32 s48, s48, s30
	s_mov_b32 s0, s48
	s_mul_i32 s2, s0, 0x4ed
	s_lshr_b32 s2, s2, 17
	s_mul_i32 s3, s2, 0x68
	s_sub_u32 s3, s0, s3
	s_mul_i32 s14, s2, 0x340000
	s_lshl_b32 s0, s3, 8
	s_add_u32 s14, s14, s0
	s_add_u32 s6, s16, s14
	s_addc_u32 s7, s17, 0
	s_lshl_b32 s14, s3, 17
	s_lshl_b32 s0, s2, 8
	s_add_u32 s14, s14, s0
	s_add_u32 s12, s44, s14
	s_addc_u32 s13, s45, 0
	s_movk_i32 s18, 0x6800
	s_movk_i32 s19, 0x800
	v_mul_lo_u32 v122, v116, s19
	v_add_u32_e32 v122, v122, v117
	s_waitcnt lgkmcnt(0)
	v_cvt_pk_bf16_f32 v104, v88, v89
	v_cvt_pk_bf16_f32 v105, v90, v91
	v_cvt_pk_bf16_f32 v106, v92, v93
	v_cvt_pk_bf16_f32 v107, v94, v95
	v_cvt_pk_bf16_f32 v108, v96, v97
	v_cvt_pk_bf16_f32 v109, v98, v99
	v_cvt_pk_bf16_f32 v110, v100, v101
	v_cvt_pk_bf16_f32 v111, v102, v103
	global_store_dwordx4 v122, v[104:107], s[12:13]
	global_store_dwordx4 v122, v[108:111], s[12:13] offset:16
	s_nop 1
	s_mul_i32 s48, s31, 7
	s_add_u32 s48, s48, s36
	s_cmp_gt_u32 s48, s30
	s_cbranch_scc1 .Lu1t_alldone
	s_mul_i32 s48, s31, 10
	s_add_u32 s48, s48, s36
	s_min_u32 s48, s48, s30
	s_mov_b32 s0, s48
	s_mul_i32 s2, s0, 0x4ed
	s_lshr_b32 s2, s2, 17
	s_mul_i32 s3, s2, 0x68
	s_sub_u32 s3, s0, s3
	s_mul_i32 s14, s2, 0x340000
	s_lshl_b32 s0, s3, 8
	s_add_u32 s14, s14, s0
	s_add_u32 s6, s16, s14
	s_addc_u32 s7, s17, 0
	s_lshl_b32 s14, s3, 17
	s_lshl_b32 s0, s2, 8
	s_add_u32 s14, s14, s0
	s_add_u32 s12, s44, s14
	s_addc_u32 s13, s45, 0
	s_movk_i32 s18, 0x6800
	s_movk_i32 s19, 0x800
	v_mul_lo_u32 v123, v112, s18
	v_add_u32_e32 v118, v123, v113
	s_lshl_b32 vcc_lo, s18, 5
	v_add_u32_e32 v119, vcc_lo, v118
	v_add_u32_e32 v120, vcc_lo, v119
	v_add_u32_e32 v121, vcc_lo, v120
	global_load_dwordx4 v[72:75], v118, s[6:7]
	global_load_dwordx4 v[76:79], v119, s[6:7]
	global_load_dwordx4 v[80:83], v120, s[6:7]
	global_load_dwordx4 v[84:87], v121, s[6:7]
	s_waitcnt vmcnt(18)
	ds_write_b32 v114, v124 offset:33792
	ds_write_b32 v114, v125 offset:33796
	ds_write_b32 v114, v126 offset:33800
	ds_write_b32 v114, v127 offset:33804
	ds_write_b32 v114, v128 offset:42112
	ds_write_b32 v114, v129 offset:42116
	ds_write_b32 v114, v130 offset:42120
	ds_write_b32 v114, v131 offset:42124
	ds_write_b32 v114, v132 offset:50432
	ds_write_b32 v114, v133 offset:50436
	ds_write_b32 v114, v134 offset:50440
	ds_write_b32 v114, v135 offset:50444
	ds_write_b32 v114, v136 offset:58752
	ds_write_b32 v114, v137 offset:58756
	ds_write_b32 v114, v138 offset:58760
	ds_write_b32 v114, v139 offset:58764
	s_waitcnt lgkmcnt(0)
	s_barrier
	ds_read_b32 v88, v115 offset:33792
	ds_read_b32 v89, v115 offset:34052
	ds_read_b32 v90, v115 offset:34312
	ds_read_b32 v91, v115 offset:34572
	ds_read_b32 v92, v115 offset:34832
	ds_read_b32 v93, v115 offset:35092
	ds_read_b32 v94, v115 offset:35352
	ds_read_b32 v95, v115 offset:35612
	ds_read_b32 v96, v115 offset:35872
	ds_read_b32 v97, v115 offset:36132
	ds_read_b32 v98, v115 offset:36392
	ds_read_b32 v99, v115 offset:36652
	ds_read_b32 v100, v115 offset:36912
	ds_read_b32 v101, v115 offset:37172
	ds_read_b32 v102, v115 offset:37432
	ds_read_b32 v103, v115 offset:37692
	s_mul_i32 s48, s31, 7
	s_add_u32 s48, s48, s36
	s_min_u32 s48, s48, s30
	s_mov_b32 s0, s48
	s_mul_i32 s2, s0, 0x4ed
	s_lshr_b32 s2, s2, 17
	s_mul_i32 s3, s2, 0x68
	s_sub_u32 s3, s0, s3
	s_mul_i32 s14, s2, 0x340000
	s_lshl_b32 s0, s3, 8
	s_add_u32 s14, s14, s0
	s_add_u32 s6, s16, s14
	s_addc_u32 s7, s17, 0
	s_lshl_b32 s14, s3, 17
	s_lshl_b32 s0, s2, 8
	s_add_u32 s14, s14, s0
	s_add_u32 s12, s44, s14
	s_addc_u32 s13, s45, 0
	s_movk_i32 s18, 0x6800
	s_movk_i32 s19, 0x800
	v_mul_lo_u32 v122, v116, s19
	v_add_u32_e32 v122, v122, v117
	s_waitcnt lgkmcnt(0)
	v_cvt_pk_bf16_f32 v104, v88, v89
	v_cvt_pk_bf16_f32 v105, v90, v91
	v_cvt_pk_bf16_f32 v106, v92, v93
	v_cvt_pk_bf16_f32 v107, v94, v95
	v_cvt_pk_bf16_f32 v108, v96, v97
	v_cvt_pk_bf16_f32 v109, v98, v99
	v_cvt_pk_bf16_f32 v110, v100, v101
	v_cvt_pk_bf16_f32 v111, v102, v103
	global_store_dwordx4 v122, v[104:107], s[12:13]
	global_store_dwordx4 v122, v[108:111], s[12:13] offset:16
	s_nop 1
	s_mul_i32 s48, s31, 8
	s_add_u32 s48, s48, s36
	s_cmp_gt_u32 s48, s30
	s_cbranch_scc1 .Lu1t_alldone
	s_mul_i32 s48, s31, 11
	s_add_u32 s48, s48, s36
	s_min_u32 s48, s48, s30
	s_mov_b32 s0, s48
	s_mul_i32 s2, s0, 0x4ed
	s_lshr_b32 s2, s2, 17
	s_mul_i32 s3, s2, 0x68
	s_sub_u32 s3, s0, s3
	s_mul_i32 s14, s2, 0x340000
	s_lshl_b32 s0, s3, 8
	s_add_u32 s14, s14, s0
	s_add_u32 s6, s16, s14
	s_addc_u32 s7, s17, 0
	s_lshl_b32 s14, s3, 17
	s_lshl_b32 s0, s2, 8
	s_add_u32 s14, s14, s0
	s_add_u32 s12, s44, s14
	s_addc_u32 s13, s45, 0
	s_movk_i32 s18, 0x6800
	s_movk_i32 s19, 0x800
	v_mul_lo_u32 v123, v112, s18
	v_add_u32_e32 v118, v123, v113
	s_lshl_b32 vcc_lo, s18, 5
	v_add_u32_e32 v119, vcc_lo, v118
	v_add_u32_e32 v120, vcc_lo, v119
	v_add_u32_e32 v121, vcc_lo, v120
	global_load_dwordx4 v[124:127], v118, s[6:7]
	global_load_dwordx4 v[128:131], v119, s[6:7]
	global_load_dwordx4 v[132:135], v120, s[6:7]
	global_load_dwordx4 v[136:139], v121, s[6:7]
	s_waitcnt vmcnt(18)
	ds_write_b32 v114, v40 offset:0
	ds_write_b32 v114, v41 offset:4
	ds_write_b32 v114, v42 offset:8
	ds_write_b32 v114, v43 offset:12
	ds_write_b32 v114, v44 offset:8320
	ds_write_b32 v114, v45 offset:8324
	ds_write_b32 v114, v46 offset:8328
	ds_write_b32 v114, v47 offset:8332
	ds_write_b32 v114, v48 offset:16640
	ds_write_b32 v114, v49 offset:16644
	ds_write_b32 v114, v50 offset:16648
	ds_write_b32 v114, v51 offset:16652
	ds_write_b32 v114, v52 offset:24960
	ds_write_b32 v114, v53 offset:24964
	ds_write_b32 v114, v54 offset:24968
	ds_write_b32 v114, v55 offset:24972
	s_waitcnt lgkmcnt(0)
	s_barrier
	ds_read_b32 v88, v115 offset:0
	ds_read_b32 v89, v115 offset:260
	ds_read_b32 v90, v115 offset:520
	ds_read_b32 v91, v115 offset:780
	ds_read_b32 v92, v115 offset:1040
	ds_read_b32 v93, v115 offset:1300
	ds_read_b32 v94, v115 offset:1560
	ds_read_b32 v95, v115 offset:1820
	ds_read_b32 v96, v115 offset:2080
	ds_read_b32 v97, v115 offset:2340
	ds_read_b32 v98, v115 offset:2600
	ds_read_b32 v99, v115 offset:2860
	ds_read_b32 v100, v115 offset:3120
	ds_read_b32 v101, v115 offset:3380
	ds_read_b32 v102, v115 offset:3640
	ds_read_b32 v103, v115 offset:3900
	s_mul_i32 s48, s31, 8
	s_add_u32 s48, s48, s36
	s_min_u32 s48, s48, s30
	s_mov_b32 s0, s48
	s_mul_i32 s2, s0, 0x4ed
	s_lshr_b32 s2, s2, 17
	s_mul_i32 s3, s2, 0x68
	s_sub_u32 s3, s0, s3
	s_mul_i32 s14, s2, 0x340000
	s_lshl_b32 s0, s3, 8
	s_add_u32 s14, s14, s0
	s_add_u32 s6, s16, s14
	s_addc_u32 s7, s17, 0
	s_lshl_b32 s14, s3, 17
	s_lshl_b32 s0, s2, 8
	s_add_u32 s14, s14, s0
	s_add_u32 s12, s44, s14
	s_addc_u32 s13, s45, 0
	s_movk_i32 s18, 0x6800
	s_movk_i32 s19, 0x800
	v_mul_lo_u32 v122, v116, s19
	v_add_u32_e32 v122, v122, v117
	s_waitcnt lgkmcnt(0)
	v_cvt_pk_bf16_f32 v104, v88, v89
	v_cvt_pk_bf16_f32 v105, v90, v91
	v_cvt_pk_bf16_f32 v106, v92, v93
	v_cvt_pk_bf16_f32 v107, v94, v95
	v_cvt_pk_bf16_f32 v108, v96, v97
	v_cvt_pk_bf16_f32 v109, v98, v99
	v_cvt_pk_bf16_f32 v110, v100, v101
	v_cvt_pk_bf16_f32 v111, v102, v103
	global_store_dwordx4 v122, v[104:107], s[12:13]
	global_store_dwordx4 v122, v[108:111], s[12:13] offset:16
	s_nop 1
	s_mul_i32 s48, s31, 9
	s_add_u32 s48, s48, s36
	s_cmp_gt_u32 s48, s30
	s_cbranch_scc1 .Lu1t_alldone
	s_mul_i32 s48, s31, 12
	s_add_u32 s48, s48, s36
	s_min_u32 s48, s48, s30
	s_mov_b32 s0, s48
	s_mul_i32 s2, s0, 0x4ed
	s_lshr_b32 s2, s2, 17
	s_mul_i32 s3, s2, 0x68
	s_sub_u32 s3, s0, s3
	s_mul_i32 s14, s2, 0x340000
	s_lshl_b32 s0, s3, 8
	s_add_u32 s14, s14, s0
	s_add_u32 s6, s16, s14
	s_addc_u32 s7, s17, 0
	s_lshl_b32 s14, s3, 17
	s_lshl_b32 s0, s2, 8
	s_add_u32 s14, s14, s0
	s_add_u32 s12, s44, s14
	s_addc_u32 s13, s45, 0
	s_movk_i32 s18, 0x6800
	s_movk_i32 s19, 0x800
	v_mul_lo_u32 v123, v112, s18
	v_add_u32_e32 v118, v123, v113
	s_lshl_b32 vcc_lo, s18, 5
	v_add_u32_e32 v119, vcc_lo, v118
	v_add_u32_e32 v120, vcc_lo, v119
	v_add_u32_e32 v121, vcc_lo, v120
	global_load_dwordx4 v[40:43], v118, s[6:7]
	global_load_dwordx4 v[44:47], v119, s[6:7]
	global_load_dwordx4 v[48:51], v120, s[6:7]
	global_load_dwordx4 v[52:55], v121, s[6:7]
	s_waitcnt vmcnt(18)
	ds_write_b32 v114, v56 offset:33792
	ds_write_b32 v114, v57 offset:33796
	ds_write_b32 v114, v58 offset:33800
	ds_write_b32 v114, v59 offset:33804
	ds_write_b32 v114, v60 offset:42112
	ds_write_b32 v114, v61 offset:42116
	ds_write_b32 v114, v62 offset:42120
	ds_write_b32 v114, v63 offset:42124
	ds_write_b32 v114, v64 offset:50432
	ds_write_b32 v114, v65 offset:50436
	ds_write_b32 v114, v66 offset:50440
	ds_write_b32 v114, v67 offset:50444
	ds_write_b32 v114, v68 offset:58752
	ds_write_b32 v114, v69 offset:58756
	ds_write_b32 v114, v70 offset:58760
	ds_write_b32 v114, v71 offset:58764
	s_waitcnt lgkmcnt(0)
	s_barrier
	ds_read_b32 v88, v115 offset:33792
	ds_read_b32 v89, v115 offset:34052
	ds_read_b32 v90, v115 offset:34312
	ds_read_b32 v91, v115 offset:34572
	ds_read_b32 v92, v115 offset:34832
	ds_read_b32 v93, v115 offset:35092
	ds_read_b32 v94, v115 offset:35352
	ds_read_b32 v95, v115 offset:35612
	ds_read_b32 v96, v115 offset:35872
	ds_read_b32 v97, v115 offset:36132
	ds_read_b32 v98, v115 offset:36392
	ds_read_b32 v99, v115 offset:36652
	ds_read_b32 v100, v115 offset:36912
	ds_read_b32 v101, v115 offset:37172
	ds_read_b32 v102, v115 offset:37432
	ds_read_b32 v103, v115 offset:37692
	s_mul_i32 s48, s31, 9
	s_add_u32 s48, s48, s36
	s_min_u32 s48, s48, s30
	s_mov_b32 s0, s48
	s_mul_i32 s2, s0, 0x4ed
	s_lshr_b32 s2, s2, 17
	s_mul_i32 s3, s2, 0x68
	s_sub_u32 s3, s0, s3
	s_mul_i32 s14, s2, 0x340000
	s_lshl_b32 s0, s3, 8
	s_add_u32 s14, s14, s0
	s_add_u32 s6, s16, s14
	s_addc_u32 s7, s17, 0
	s_lshl_b32 s14, s3, 17
	s_lshl_b32 s0, s2, 8
	s_add_u32 s14, s14, s0
	s_add_u32 s12, s44, s14
	s_addc_u32 s13, s45, 0
	s_movk_i32 s18, 0x6800
	s_movk_i32 s19, 0x800
	v_mul_lo_u32 v122, v116, s19
	v_add_u32_e32 v122, v122, v117
	s_waitcnt lgkmcnt(0)
	v_cvt_pk_bf16_f32 v104, v88, v89
	v_cvt_pk_bf16_f32 v105, v90, v91
	v_cvt_pk_bf16_f32 v106, v92, v93
	v_cvt_pk_bf16_f32 v107, v94, v95
	v_cvt_pk_bf16_f32 v108, v96, v97
	v_cvt_pk_bf16_f32 v109, v98, v99
	v_cvt_pk_bf16_f32 v110, v100, v101
	v_cvt_pk_bf16_f32 v111, v102, v103
	global_store_dwordx4 v122, v[104:107], s[12:13]
	global_store_dwordx4 v122, v[108:111], s[12:13] offset:16
	s_nop 1
	s_mul_i32 s48, s31, 10
	s_add_u32 s48, s48, s36
	s_cmp_gt_u32 s48, s30
	s_cbranch_scc1 .Lu1t_alldone
	s_waitcnt vmcnt(14)
	ds_write_b32 v114, v72 offset:0
	ds_write_b32 v114, v73 offset:4
	ds_write_b32 v114, v74 offset:8
	ds_write_b32 v114, v75 offset:12
	ds_write_b32 v114, v76 offset:8320
	ds_write_b32 v114, v77 offset:8324
	ds_write_b32 v114, v78 offset:8328
	ds_write_b32 v114, v79 offset:8332
	ds_write_b32 v114, v80 offset:16640
	ds_write_b32 v114, v81 offset:16644
	ds_write_b32 v114, v82 offset:16648
	ds_write_b32 v114, v83 offset:16652
	ds_write_b32 v114, v84 offset:24960
	ds_write_b32 v114, v85 offset:24964
	ds_write_b32 v114, v86 offset:24968
	ds_write_b32 v114, v87 offset:24972
	s_waitcnt lgkmcnt(0)
	s_barrier
	ds_read_b32 v88, v115 offset:0
	ds_read_b32 v89, v115 offset:260
	ds_read_b32 v90, v115 offset:520
	ds_read_b32 v91, v115 offset:780
	ds_read_b32 v92, v115 offset:1040
	ds_read_b32 v93, v115 offset:1300
	ds_read_b32 v94, v115 offset:1560
	ds_read_b32 v95, v115 offset:1820
	ds_read_b32 v96, v115 offset:2080
	ds_read_b32 v97, v115 offset:2340
	ds_read_b32 v98, v115 offset:2600
	ds_read_b32 v99, v115 offset:2860
	ds_read_b32 v100, v115 offset:3120
	ds_read_b32 v101, v115 offset:3380
	ds_read_b32 v102, v115 offset:3640
	ds_read_b32 v103, v115 offset:3900
	s_mul_i32 s48, s31, 10
	s_add_u32 s48, s48, s36
	s_min_u32 s48, s48, s30
	s_mov_b32 s0, s48
	s_mul_i32 s2, s0, 0x4ed
	s_lshr_b32 s2, s2, 17
	s_mul_i32 s3, s2, 0x68
	s_sub_u32 s3, s0, s3
	s_mul_i32 s14, s2, 0x340000
	s_lshl_b32 s0, s3, 8
	s_add_u32 s14, s14, s0
	s_add_u32 s6, s16, s14
	s_addc_u32 s7, s17, 0
	s_lshl_b32 s14, s3, 17
	s_lshl_b32 s0, s2, 8
	s_add_u32 s14, s14, s0
	s_add_u32 s12, s44, s14
	s_addc_u32 s13, s45, 0
	s_movk_i32 s18, 0x6800
	s_movk_i32 s19, 0x800
	v_mul_lo_u32 v122, v116, s19
	v_add_u32_e32 v122, v122, v117
	s_waitcnt lgkmcnt(0)
	v_cvt_pk_bf16_f32 v104, v88, v89
	v_cvt_pk_bf16_f32 v105, v90, v91
	v_cvt_pk_bf16_f32 v106, v92, v93
	v_cvt_pk_bf16_f32 v107, v94, v95
	v_cvt_pk_bf16_f32 v108, v96, v97
	v_cvt_pk_bf16_f32 v109, v98, v99
	v_cvt_pk_bf16_f32 v110, v100, v101
	v_cvt_pk_bf16_f32 v111, v102, v103
	global_store_dwordx4 v122, v[104:107], s[12:13]
	global_store_dwordx4 v122, v[108:111], s[12:13] offset:16
	s_nop 1
	s_mul_i32 s48, s31, 11
	s_add_u32 s48, s48, s36
	s_cmp_gt_u32 s48, s30
	s_cbranch_scc1 .Lu1t_alldone
	s_waitcnt vmcnt(10)
	ds_write_b32 v114, v124 offset:33792
	ds_write_b32 v114, v125 offset:33796
	ds_write_b32 v114, v126 offset:33800
	ds_write_b32 v114, v127 offset:33804
	ds_write_b32 v114, v128 offset:42112
	ds_write_b32 v114, v129 offset:42116
	ds_write_b32 v114, v130 offset:42120
	ds_write_b32 v114, v131 offset:42124
	ds_write_b32 v114, v132 offset:50432
	ds_write_b32 v114, v133 offset:50436
	ds_write_b32 v114, v134 offset:50440
	ds_write_b32 v114, v135 offset:50444
	ds_write_b32 v114, v136 offset:58752
	ds_write_b32 v114, v137 offset:58756
	ds_write_b32 v114, v138 offset:58760
	ds_write_b32 v114, v139 offset:58764
	s_waitcnt lgkmcnt(0)
	s_barrier
	ds_read_b32 v88, v115 offset:33792
	ds_read_b32 v89, v115 offset:34052
	ds_read_b32 v90, v115 offset:34312
	ds_read_b32 v91, v115 offset:34572
	ds_read_b32 v92, v115 offset:34832
	ds_read_b32 v93, v115 offset:35092
	ds_read_b32 v94, v115 offset:35352
	ds_read_b32 v95, v115 offset:35612
	ds_read_b32 v96, v115 offset:35872
	ds_read_b32 v97, v115 offset:36132
	ds_read_b32 v98, v115 offset:36392
	ds_read_b32 v99, v115 offset:36652
	ds_read_b32 v100, v115 offset:36912
	ds_read_b32 v101, v115 offset:37172
	ds_read_b32 v102, v115 offset:37432
	ds_read_b32 v103, v115 offset:37692
	s_mul_i32 s48, s31, 11
	s_add_u32 s48, s48, s36
	s_min_u32 s48, s48, s30
	s_mov_b32 s0, s48
	s_mul_i32 s2, s0, 0x4ed
	s_lshr_b32 s2, s2, 17
	s_mul_i32 s3, s2, 0x68
	s_sub_u32 s3, s0, s3
	s_mul_i32 s14, s2, 0x340000
	s_lshl_b32 s0, s3, 8
	s_add_u32 s14, s14, s0
	s_add_u32 s6, s16, s14
	s_addc_u32 s7, s17, 0
	s_lshl_b32 s14, s3, 17
	s_lshl_b32 s0, s2, 8
	s_add_u32 s14, s14, s0
	s_add_u32 s12, s44, s14
	s_addc_u32 s13, s45, 0
	s_movk_i32 s18, 0x6800
	s_movk_i32 s19, 0x800
	v_mul_lo_u32 v122, v116, s19
	v_add_u32_e32 v122, v122, v117
	s_waitcnt lgkmcnt(0)
	v_cvt_pk_bf16_f32 v104, v88, v89
	v_cvt_pk_bf16_f32 v105, v90, v91
	v_cvt_pk_bf16_f32 v106, v92, v93
	v_cvt_pk_bf16_f32 v107, v94, v95
	v_cvt_pk_bf16_f32 v108, v96, v97
	v_cvt_pk_bf16_f32 v109, v98, v99
	v_cvt_pk_bf16_f32 v110, v100, v101
	v_cvt_pk_bf16_f32 v111, v102, v103
	global_store_dwordx4 v122, v[104:107], s[12:13]
	global_store_dwordx4 v122, v[108:111], s[12:13] offset:16
	s_nop 1
	s_mul_i32 s48, s31, 12
	s_add_u32 s48, s48, s36
	s_cmp_gt_u32 s48, s30
	s_cbranch_scc1 .Lu1t_alldone
	s_waitcnt vmcnt(6)
	ds_write_b32 v114, v40 offset:0
	ds_write_b32 v114, v41 offset:4
	ds_write_b32 v114, v42 offset:8
	ds_write_b32 v114, v43 offset:12
	ds_write_b32 v114, v44 offset:8320
	ds_write_b32 v114, v45 offset:8324
	ds_write_b32 v114, v46 offset:8328
	ds_write_b32 v114, v47 offset:8332
	ds_write_b32 v114, v48 offset:16640
	ds_write_b32 v114, v49 offset:16644
	ds_write_b32 v114, v50 offset:16648
	ds_write_b32 v114, v51 offset:16652
	ds_write_b32 v114, v52 offset:24960
	ds_write_b32 v114, v53 offset:24964
	ds_write_b32 v114, v54 offset:24968
	ds_write_b32 v114, v55 offset:24972
	s_waitcnt lgkmcnt(0)
	s_barrier
	ds_read_b32 v88, v115 offset:0
	ds_read_b32 v89, v115 offset:260
	ds_read_b32 v90, v115 offset:520
	ds_read_b32 v91, v115 offset:780
	ds_read_b32 v92, v115 offset:1040
	ds_read_b32 v93, v115 offset:1300
	ds_read_b32 v94, v115 offset:1560
	ds_read_b32 v95, v115 offset:1820
	ds_read_b32 v96, v115 offset:2080
	ds_read_b32 v97, v115 offset:2340
	ds_read_b32 v98, v115 offset:2600
	ds_read_b32 v99, v115 offset:2860
	ds_read_b32 v100, v115 offset:3120
	ds_read_b32 v101, v115 offset:3380
	ds_read_b32 v102, v115 offset:3640
	ds_read_b32 v103, v115 offset:3900
	s_mul_i32 s48, s31, 12
	s_add_u32 s48, s48, s36
	s_min_u32 s48, s48, s30
	s_mov_b32 s0, s48
	s_mul_i32 s2, s0, 0x4ed
	s_lshr_b32 s2, s2, 17
	s_mul_i32 s3, s2, 0x68
	s_sub_u32 s3, s0, s3
	s_mul_i32 s14, s2, 0x340000
	s_lshl_b32 s0, s3, 8
	s_add_u32 s14, s14, s0
	s_add_u32 s6, s16, s14
	s_addc_u32 s7, s17, 0
	s_lshl_b32 s14, s3, 17
	s_lshl_b32 s0, s2, 8
	s_add_u32 s14, s14, s0
	s_add_u32 s12, s44, s14
	s_addc_u32 s13, s45, 0
	s_movk_i32 s18, 0x6800
	s_movk_i32 s19, 0x800
	v_mul_lo_u32 v122, v116, s19
	v_add_u32_e32 v122, v122, v117
	s_waitcnt lgkmcnt(0)
	v_cvt_pk_bf16_f32 v104, v88, v89
	v_cvt_pk_bf16_f32 v105, v90, v91
	v_cvt_pk_bf16_f32 v106, v92, v93
	v_cvt_pk_bf16_f32 v107, v94, v95
	v_cvt_pk_bf16_f32 v108, v96, v97
	v_cvt_pk_bf16_f32 v109, v98, v99
	v_cvt_pk_bf16_f32 v110, v100, v101
	v_cvt_pk_bf16_f32 v111, v102, v103
	global_store_dwordx4 v122, v[104:107], s[12:13]
	global_store_dwordx4 v122, v[108:111], s[12:13] offset:16
	s_nop 1

.Ln1t_entry:
	v_readlane_b32 s0, v254, 4
	s_cmpk_eq_u32 s0, 0x100
	s_cbranch_scc1 .LBB0_692
	v_readlane_b32 s68, v254, 38
	v_readlane_b32 s69, v254, 39
	v_readlane_b32 s70, v254, 48
	v_readlane_b32 s71, v254, 49
	s_nop 3
	s_add_u32 s68, s68, 0x1a00000
	s_addc_u32 s69, s69, 0
	s_mov_b32 s73, s21
	s_mov_b32 s74, s10
	s_cmpk_gt_i32 s74, 0x33f
	s_cbranch_scc1 .LBB0_692
	s_mov_b32 s72, s74
